# attention work queues: static first units arranged so the two waves of a SIMD start with one heavy and one light unit (octile w with octile 7-w), on top of v29
# baseline (speedup 1.0000x reference)
.LBB0_346:
	s_or_b64 exec, exec, s[4:5]
	s_xor_b64 s[46:47], s[0:1], -1
	s_lshl_b32 s0, s48, 9
	v_readlane_b32 s1, v254, 57
	s_or_b32 s76, s0, s1
	v_mov_b32_e32 v0, v236
	s_mov_b64 s[0:1], s[38:39]
	s_waitcnt lgkmcnt(0)
	s_barrier
	s_load_dwordx2 s[4:5], s[0:1], 0x80
	v_readfirstlane_b32 s3, v0
	s_lshl_b32 s3, s3, 8
	s_and_b32 s3, s3, 0xffffc000
	s_add_i32 s49, s3, 0
	s_lshl_b64 s[6:7], s[76:77], 2
	s_waitcnt lgkmcnt(0)
	s_add_u32 s3, s4, s6
	s_addc_u32 s4, s5, s7
	v_readlane_b32 s5, v254, 27
	v_and_b32_e32 v246, 63, v0
	s_add_u32 s40, s3, s5
	s_addc_u32 s41, s4, 0
	v_cmp_eq_u32_e64 s[18:19], 0, v246
	v_readfirstlane_b32 s99, v236
	s_lshr_b32 s99, s99, 6
	s_sub_i32 s100, 11, s99
	s_cmp_ge_u32 s99, 4
	s_cselect_b32 s99, s100, s99
	s_lshl_b32 s99, s99, 5
	s_lshr_b32 s100, s2, 3
	s_add_i32 s99, s99, s100
	s_branch .LBB0_350
